# v12 plus phase-0 barrier: cooperative-groups grid sync replaced by a clone of the kernel's own XCD-hierarchical barrier
# speedup vs baseline: 1.0059x; 1.0059x over previous
; __device__ __forceinline__ unsigned xb_ld(unsigned* p)              { return __hip_atomic_load(p, __ATOMIC_RELAXED, __HIP_MEMORY_SCOPE_AGENT); }
; __device__ __forceinline__ void xcd_barrier_complete(unsigned* bar, unsigned x, unsigned& nloc, unsigned& nx) {
;     const unsigned G = gridDim.x * gridDim.y * gridDim.z;
;     unsigned sum, cnt, mine, sp = 0u;
;     for (;;) {
;         sum = 0u; cnt = 0u; mine = 0u;
; #pragma unroll
;         for (unsigned j = 0; j < 16; ++j) { const unsigned c = xb_ld(&bar[XB_XCNT(j)]); sum += c; cnt += (c > 0u) ? 1u : 0u; mine = (j == x) ? c : mine; }
; __device__ __forceinline__ void xcd_barrier(const XcdBarrier& b) {
;     asm volatile("s_waitcnt vmcnt(0)" ::: "memory");
;     __syncthreads();
;     if (threadIdx.x == 0) {
;         unsigned* bar = b.bar;
;         __builtin_amdgcn_s_waitcnt(0);
;         unsigned nloc = b.st[0], nx = b.st[1];
;         if (nloc == 0u) { xcd_barrier_complete(bar, b.x, nloc, nx); b.st[0] = nloc; b.st[1] = nx; }
.LBB0_406:
	s_or_b64 exec, exec, s[2:3]
	s_cmp_lt_i32 s95, 2
	s_cbranch_scc1 .LBB0_418
.Lxb0_682:
	s_waitcnt vmcnt(0)
	s_waitcnt vmcnt(0) lgkmcnt(0)
	s_barrier
	s_mov_b64 s[0:1], exec
	v_readlane_b32 s2, v247, 5
	v_readlane_b32 s3, v247, 6
	s_and_b64 s[2:3], s[0:1], s[2:3]
	s_mov_b64 exec, s[2:3]
	s_cbranch_execz .Lxb0_734
	s_add_i32 s2, 0, 0x27ff0
	v_mov_b32_e32 v0, s2
	s_waitcnt vmcnt(0) expcnt(0) lgkmcnt(0)
	ds_read_b32 v2, v0
	s_add_i32 s2, 0, 0x27ff4
	v_mov_b32_e32 v0, s2
	ds_read_b32 v0, v0
	s_waitcnt lgkmcnt(1)
	v_cmp_ne_u32_e32 vcc, 0, v2
	s_cbranch_vccnz .Lxb0_698
	v_readlane_b32 s2, v247, 4
	s_mul_i32 s20, s85, s2
	s_add_u32 s2, s96, 0x1f1ede00
	s_addc_u32 s3, s97, 0
	s_add_u32 s4, s96, 0x1f1ee000
	s_addc_u32 s5, s97, 0
	s_add_u32 s6, s96, 0x1f1ee100
	s_addc_u32 s7, s97, 0
	s_add_u32 s8, s96, 0x1f1ee200
	s_addc_u32 s9, s97, 0
	s_add_u32 s10, s96, 0x1f1ee300
	s_addc_u32 s11, s97, 0
	s_add_u32 s12, s96, 0x1f1ee400
	s_addc_u32 s13, s97, 0
	s_add_u32 s14, s96, 0x1f1ee500
	s_addc_u32 s15, s97, 0
	s_add_u32 s16, s96, 0x1f1ee600
	s_addc_u32 s17, s97, 0
	s_add_u32 s18, s96, 0x1f1ee700
	s_addc_u32 s19, s97, 0
	s_add_u32 s28, s96, 0x1f1ee800
	s_addc_u32 s29, s97, 0
	s_add_u32 s30, s96, 0x1f1ee900
	s_addc_u32 s31, s97, 0
	s_add_u32 s34, s96, 0x1f1eea00
	s_addc_u32 s35, s97, 0
	s_add_u32 s36, s96, 0x1f1eeb00
	s_addc_u32 s37, s97, 0
	s_add_u32 s38, s96, 0x1f1eec00
	s_addc_u32 s39, s97, 0
	s_add_u32 s40, s96, 0x1f1eed00
	s_addc_u32 s41, s97, 0
	s_add_u32 s42, s96, 0x1f1eee00
	s_addc_u32 s43, s97, 0
	s_add_u32 s44, s96, 0x1f1eef00
	s_mul_i32 s20, s20, s84
	s_addc_u32 s45, s97, 0
	s_mov_b32 s21, 1
	v_mov_b32_e32 v16, 0
	s_branch .Lxb0_686

; __device__ __forceinline__ unsigned xb_ld(unsigned* p)              { return __hip_atomic_load(p, __ATOMIC_RELAXED, __HIP_MEMORY_SCOPE_AGENT); }
; #define XB_SPIN(cond, bar) do { unsigned _sp = 0; while (cond) { __builtin_amdgcn_s_sleep(1); \
;     if ((++_sp & 255u) == 0u) { if (xb_ld(&(bar)[XB_TMO])) break; if (_sp > XB_SPIN_CAP) { atomicAdd(&(bar)[XB_TMO], 1u); break; } } } } while (0)
; __device__ __forceinline__ void xcd_barrier(const XcdBarrier& b) {
;     ...
;             XB_SPIN(xb_ld(&bar[XB_XGEN(b.x)]) == gen, bar);
;             __builtin_amdgcn_fence(__ATOMIC_ACQUIRE, "agent");
;             asm volatile("s_waitcnt vmcnt(0)" ::: "memory");
;         }
;     }
;     __syncthreads();
;   __device__ bool next(int i, Unit& u) const {
;     const long L = (long)i * G + c; if (L >= cnt) return false;
;     int wgid = t0 + (int)L / ks; u.koff = ((int)L % ks) * klen; u.seq = (int)L;
;     { const int q = nwg / NXCD, r = nwg % NXCD, xcd = wgid % NXCD, off = wgid / NXCD; wgid = (xcd < r ? xcd * (q + 1) : r * (q + 1) + (xcd - r) * q) + off; }
;     const int nig = WGM * nN, gid = wgid / nig, fm = gid * WGM, gsz = (nM - fm) < WGM ? (nM - fm) : WGM;
;     u.pm = fm + ((wgid % nig) % gsz); u.pn = (wgid % nig) / gsz; return true;
.Lxb0_734:
	s_or_b64 exec, exec, s[0:1]
	s_waitcnt lgkmcnt(0)
	s_barrier
.LBB0_418:
	v_writelane_b32 v247, s92, 56
	s_cmp_gt_i32 s94, 1
	s_cselect_b64 s[0:1], -1, 0
	v_writelane_b32 v247, s93, 57
	s_cmp_lt_i32 s95, 2
	v_writelane_b32 v247, s94, 58
	s_cselect_b64 s[2:3], -1, 0
	s_or_b64 s[0:1], s[0:1], s[2:3]
	v_writelane_b32 v247, s95, 59
	v_writelane_b32 v247, s96, 60
	s_and_b64 vcc, exec, s[0:1]
	s_nop 0
	v_writelane_b32 v247, s97, 61
	v_writelane_b32 v247, s54, 62
	s_cbranch_vccnz .LBB0_735
	v_mov_b32_e32 v8, v224
	s_cmpk_lt_i32 s54, 0x6c1
	s_cselect_b64 s[2:3], -1, 0
	s_cmpk_gt_i32 s54, 0x6c0
	v_readfirstlane_b32 s20, v8
	s_cbranch_scc1 .LBB0_422
	s_ashr_i32 s0, s54, 31
	s_lshr_b32 s0, s0, 29
	s_add_i32 s4, s54, s0
	s_and_b32 s0, s4, -8
	s_sub_i32 s5, s54, s0
	s_cmp_gt_i32 s5, 0
	s_cbranch_scc0 .LBB0_678
	s_mul_i32 s0, s5, 0xd8
	s_or_b32 s6, s0, 1
	s_cbranch_execz .LBB0_679
	s_branch .LBB0_680
